# sample-MLA: score-computing wave runs its whole step at priority 3 (its partner at 0/1)
# speedup vs baseline: 1.0053x; 1.0053x over previous
.LBB0_1110:
	s_add_i32 s19, s92, s18
	s_barrier
	s_and_b32 s19, s19, 1
	s_cmp_lg_u32 s3, s19
	s_cselect_b64 s[66:67], -1, 0
	s_cmp_eq_u32 s3, s19
	s_cbranch_scc1 .LBB0_1112
	s_setprio 3
	s_nop 0
	ds_read_b128 v[138:141], v223
	ds_read_b128 v[134:137], v223 offset:16

.Lpv_prio_done:
	ds_read_b64_tr_b16 v[204:205], v200 offset:1536
	ds_read_b64_tr_b16 v[206:207], v200 offset:9728
	s_waitcnt lgkmcnt(6)
	v_mfma_f32_32x32x16_bf16 v[6:21], v[138:141], v[142:145], v[6:21]
	ds_read_b64_tr_b16 v[142:143], v200 offset:2048
	ds_read_b64_tr_b16 v[144:145], v200 offset:10240
	s_waitcnt lgkmcnt(6)
	v_mfma_f32_32x32x16_bf16 v[118:133], v[138:141], v[146:149], v[118:133]
	ds_read_b64_tr_b16 v[146:147], v200 offset:2560
	ds_read_b64_tr_b16 v[148:149], v200 offset:10752
	s_waitcnt lgkmcnt(6)
	v_mfma_f32_32x32x16_bf16 v[102:117], v[138:141], v[248:251], v[102:117]
	ds_read_b64_tr_b16 v[248:249], v200 offset:3072
	ds_read_b64_tr_b16 v[250:251], v200 offset:11264
	s_waitcnt lgkmcnt(6)
	v_mfma_f32_32x32x16_bf16 v[86:101], v[138:141], v[204:207], v[86:101]
	ds_read_b64_tr_b16 v[204:205], v200 offset:3584
	ds_read_b64_tr_b16 v[206:207], v200 offset:11776
	s_waitcnt lgkmcnt(6)
	v_mfma_f32_32x32x16_bf16 v[70:85], v[138:141], v[142:145], v[70:85]
	ds_read_b64_tr_b16 v[142:143], v1 offset:0
	ds_read_b64_tr_b16 v[144:145], v1 offset:8192
	s_waitcnt lgkmcnt(6)
	v_mfma_f32_32x32x16_bf16 v[54:69], v[138:141], v[146:149], v[54:69]
	ds_read_b64_tr_b16 v[146:147], v1 offset:512
	ds_read_b64_tr_b16 v[148:149], v1 offset:8704
	s_waitcnt lgkmcnt(6)
	v_mfma_f32_32x32x16_bf16 v[38:53], v[138:141], v[248:251], v[38:53]
	ds_read_b64_tr_b16 v[248:249], v1 offset:1024
	ds_read_b64_tr_b16 v[250:251], v1 offset:9216
	s_waitcnt lgkmcnt(6)
	v_mfma_f32_32x32x16_bf16 v[22:37], v[138:141], v[204:207], v[22:37]
	ds_read_b64_tr_b16 v[204:205], v1 offset:1536
	ds_read_b64_tr_b16 v[206:207], v1 offset:9728
	s_waitcnt lgkmcnt(6)
	v_mfma_f32_32x32x16_bf16 v[6:21], v[134:137], v[142:145], v[6:21]
	ds_read_b64_tr_b16 v[142:143], v1 offset:2048
	ds_read_b64_tr_b16 v[144:145], v1 offset:10240
	s_waitcnt lgkmcnt(6)
	v_mfma_f32_32x32x16_bf16 v[118:133], v[134:137], v[146:149], v[118:133]
	ds_read_b64_tr_b16 v[146:147], v1 offset:2560
	ds_read_b64_tr_b16 v[148:149], v1 offset:10752
	s_waitcnt lgkmcnt(6)
	v_mfma_f32_32x32x16_bf16 v[102:117], v[134:137], v[248:251], v[102:117]
	ds_read_b64_tr_b16 v[248:249], v1 offset:3072
	ds_read_b64_tr_b16 v[250:251], v1 offset:11264
	s_waitcnt lgkmcnt(6)
	v_mfma_f32_32x32x16_bf16 v[86:101], v[134:137], v[204:207], v[86:101]
	ds_read_b64_tr_b16 v[204:205], v1 offset:3584
	ds_read_b64_tr_b16 v[206:207], v1 offset:11776
	s_waitcnt lgkmcnt(6)
	v_mfma_f32_32x32x16_bf16 v[70:85], v[134:137], v[142:145], v[70:85]
	s_waitcnt lgkmcnt(4)
	v_mfma_f32_32x32x16_bf16 v[54:69], v[134:137], v[146:149], v[54:69]
	s_waitcnt lgkmcnt(2)
	v_mfma_f32_32x32x16_bf16 v[38:53], v[134:137], v[248:251], v[38:53]
	s_waitcnt lgkmcnt(0)
	v_mfma_f32_32x32x16_bf16 v[22:37], v[134:137], v[204:207], v[22:37]
	s_setprio 0
	s_andn2_b64 vcc, exec, s[66:67]
	s_cbranch_vccnz .LBB0_1105
	s_mul_hi_u32 s19, s1, 0xaaaaaaab
	s_lshr_b32 s19, s19, 2
	s_mul_i32 s19, s19, 0xffff0d00
	s_add_i32 s19, s19, 0
	s_add_i32 s19, s19, s81
	v_add_u32_e32 v1, s19, v242
	v_add_u32_e32 v200, s14, v1
	v_add3_u32 v134, v200, v231, v232
	v_add3_u32 v138, v200, v230, v232
	ds_read_b128 v[134:137], v134
	ds_read_b128 v[204:207], v138
	v_add3_u32 v208, v200, v228, v232
	ds_read_b128 v[248:251], v208
	s_setprio 1
	s_waitcnt lgkmcnt(2)
	v_mfma_f32_32x32x16_bf16 v[134:149], v[134:137], v[194:197], 0
	s_waitcnt lgkmcnt(1)
	v_mfma_f32_32x32x16_bf16 v[134:149], v[204:207], v[190:193], v[134:149]
	v_add3_u32 v208, v200, v227, v232
	ds_read_b128 v[204:207], v208
	s_waitcnt lgkmcnt(1)
	v_mfma_f32_32x32x16_bf16 v[134:149], v[248:251], v[186:189], v[134:149]
	v_add3_u32 v208, v200, v236, v232
	ds_read_b128 v[248:251], v208
	s_waitcnt lgkmcnt(1)
	v_mfma_f32_32x32x16_bf16 v[134:149], v[204:207], v[182:185], v[134:149]
	v_add3_u32 v208, v200, v235, v232
	ds_read_b128 v[204:207], v208
	s_waitcnt lgkmcnt(1)
	v_mfma_f32_32x32x16_bf16 v[134:149], v[248:251], v[178:181], v[134:149]
	v_add3_u32 v208, v200, v234, v232
	ds_read_b128 v[248:251], v208
	s_waitcnt lgkmcnt(1)
	v_mfma_f32_32x32x16_bf16 v[134:149], v[204:207], v[174:177], v[134:149]
	v_add3_u32 v208, v200, v233, v232
	ds_read_b128 v[204:207], v208
	s_waitcnt lgkmcnt(1)
	v_mfma_f32_32x32x16_bf16 v[134:149], v[248:251], v[170:173], v[134:149]
	v_add3_u32 v208, v1, v231, v226
	ds_read_b128 v[248:251], v208 offset:8192
	s_waitcnt lgkmcnt(1)
	v_mfma_f32_32x32x16_bf16 v[134:149], v[204:207], v[166:169], v[134:149]
	v_add3_u32 v208, v1, v230, v226
	ds_read_b128 v[204:207], v208 offset:8192
	s_waitcnt lgkmcnt(1)
	v_mfma_f32_32x32x16_bf16 v[134:149], v[248:251], v[162:165], v[134:149]
	v_add3_u32 v208, v1, v228, v226
	ds_read_b128 v[248:251], v208 offset:8192
	s_waitcnt lgkmcnt(1)
	v_mfma_f32_32x32x16_bf16 v[134:149], v[204:207], v[158:161], v[134:149]
	v_add3_u32 v208, v1, v227, v226
	ds_read_b128 v[204:207], v208 offset:8192
	s_waitcnt lgkmcnt(1)
	v_mfma_f32_32x32x16_bf16 v[134:149], v[248:251], v[154:157], v[134:149]
	s_waitcnt lgkmcnt(0)
	v_mfma_f32_32x32x16_bf16 v[134:149], v[204:207], v[150:153], v[134:149]
	s_setprio 0
	v_add_u32_e32 v1, s15, v198
	v_add_u32_e32 v208, s19, v1
	v_add_u32_e32 v1, 0x1b900, v208
	ds_read_b128 v[204:207], v1
	v_add_u32_e32 v1, 0x1b920, v208
	ds_read_b128 v[248:251], v1
	s_waitcnt lgkmcnt(1)
	s_nop 5
	v_fma_f32 v1, v134, v204, -v213
	v_fma_f32 v134, v135, v205, -v213
	v_exp_f32_e32 v1, v1
	v_fma_f32 v135, v136, v206, -v213
	v_exp_f32_e32 v200, v134
	v_fma_f32 v136, v137, v207, -v213
	v_exp_f32_e32 v204, v135
	v_exp_f32_e32 v205, v136
	s_waitcnt lgkmcnt(0)
	v_fma_f32 v135, v138, v248, -v213
	v_add_f32_e32 v134, 0, v1
	v_exp_f32_e32 v206, v135
	v_add_f32_e32 v134, v200, v134
	v_add_f32_e32 v134, v204, v134
	v_add_f32_e32 v134, v205, v134
	v_add_f32_e32 v138, v206, v134
	v_fma_f32 v134, v139, v249, -v213
	v_exp_f32_e32 v207, v134
	v_fma_f32 v134, v140, v250, -v213
	v_exp_f32_e32 v248, v134
	v_fma_f32 v134, v141, v251, -v213
	v_exp_f32_e32 v249, v134
	v_add_u32_e32 v139, 0x1e180, v208
	v_add_f32_e32 v138, v207, v138
	ds_read_b128 v[134:137], v139
	v_add_f32_e32 v138, v248, v138
	v_add_f32_e32 v208, v249, v138
	ds_read_b128 v[138:141], v139 offset:32
	s_waitcnt lgkmcnt(1)
	v_fma_f32 v134, v142, v134, -v213
	v_exp_f32_e32 v134, v134
	v_fma_f32 v135, v143, v135, -v213
	s_waitcnt lgkmcnt(0)
	v_fma_f32 v138, v146, v138, -v213
	v_exp_f32_e32 v135, v135
	v_fma_f32 v136, v144, v136, -v213
	v_exp_f32_e32 v143, v138
	v_fma_f32 v138, v147, v139, -v213
	v_exp_f32_e32 v136, v136
	v_fma_f32 v137, v145, v137, -v213
	v_exp_f32_e32 v144, v138
	v_fma_f32 v138, v148, v140, -v213
	v_exp_f32_e32 v137, v137
	v_exp_f32_e32 v145, v138
	v_fma_f32 v138, v149, v141, -v213
	v_add_f32_e32 v142, v134, v208
	v_exp_f32_e32 v146, v138
	v_add_f32_e32 v142, v135, v142
	v_add_f32_e32 v142, v136, v142
	v_add_f32_e32 v142, v137, v142
	v_cvt_pk_bf16_f32 v138, v1, v200
	v_cvt_pk_bf16_f32 v139, v204, v205
	v_cvt_pk_bf16_f32 v140, v206, v207
	v_cvt_pk_bf16_f32 v141, v248, v249
	s_nop 0
	v_permlane32_swap_b32_e32 v138, v140
	v_permlane32_swap_b32_e32 v139, v141
	v_cvt_pk_bf16_f32 v134, v134, v135
	v_cvt_pk_bf16_f32 v135, v136, v137
	v_cvt_pk_bf16_f32 v136, v143, v144
	v_cvt_pk_bf16_f32 v137, v145, v146
	v_add_f32_e32 v1, v143, v142
	v_permlane32_swap_b32_e32 v134, v136
	v_permlane32_swap_b32_e32 v135, v137
	v_add_f32_e32 v1, v144, v1
	ds_write_b128 v223, v[138:141]
	ds_write_b128 v223, v[134:137] offset:16
	v_add_f32_e32 v1, v145, v1
	s_waitcnt lgkmcnt(0)
	v_add_f32_e32 v1, v146, v1
	v_add_f32_e32 v2, v2, v1
	s_branch .LBB0_1105
	s_nop 0
	s_nop 0
	s_nop 0
	s_nop 0
	s_nop 0
	s_nop 0
	s_nop 0
	s_nop 0
	s_nop 0
	s_nop 0
.LBB0_1146:
	v_cndmask_b32_e64 v142, 0, 1, s[34:35]
	v_cmp_ne_u32_e64 s[50:51], 1, v142
	s_andn2_b64 vcc, exec, s[34:35]
	s_mov_b64 s[52:53], -1
	s_cbranch_vccnz .LBB0_1148
	s_waitcnt vmcnt(4)
	s_mov_b64 s[52:53], 0
